# GDN prep 5b: gate-wave next-unit loads issued once ahead of the direction loop (no full-latency stall at the zero-fill wait ladder)
# speedup vs baseline: 1.0053x; 1.0053x over previous
; __device__ __forceinline__ void gdn_preload(const Frame& F, int u, int t, GdnPre& P) {
;     ...
;         const int pair = t % 96, rg = t / 96, c0 = 2 * pair, part = c0 >> 6, d0 = c0 & 63, zcol = part * 256 + h * 64 + d0;
;         const int rbase = row0 + rg * 16 - 2; const bf16_t* zc = F.Z + zcol;
; #pragma unroll
;         for (int rr = 0; rr < 20; ++rr) { int row = rbase + rr; row = row < seg_lo ? seg_lo : (row >= seg_hi ? seg_hi - 1 : row); P.raw[rr] = *(const unsigned*)(zc + (size_t)row * ZW); }
;         P.ga = 0; P.gb = 0;
;     } else {
;         const int tt = t - 384, d = tt >> 6, pp = tt & 63; const bf16_t* zr = F.Z + (size_t)(row0 + pp) * ZW;
;         P.ga = zr[ZC_GA + d * 4 + h]; P.gb = zr[ZC_GB + d * 4 + h];
.LBB0_644:
	s_cmp_gt_i32 s28, 3
	s_cselect_b32 s6, s76, s77
	s_add_i32 s1, 0, 0xe000
	s_cmp_gt_i32 s28, 3
	s_cselect_b32 s7, s1, s2
	s_add_i32 s3, 0, 0x4800
	s_cmp_gt_i32 s28, 3
	v_readlane_b32 s4, v253, 56
	s_cselect_b32 s8, 0x2400, 0
	s_cselect_b32 s12, s3, s4
	s_add_i32 s4, s34, 0x100
	s_cmpk_gt_i32 s34, 0x37f
	s_cselect_b64 s[10:11], -1, 0
	s_cmpk_lt_i32 s34, 0x380
	s_cselect_b32 s13, s4, -1
	s_lshl_b32 s14, s28, 4
	s_and_b32 s14, s14, 48
	s_add_i32 s8, s8, 0
	s_mul_i32 s15, s14, 0x90
	s_add_i32 s8, s8, s15
	s_add_i32 s8, s8, 0x12800
	v_or_b32_e32 v0, s14, v17
	v_add3_u32 v63, s8, v113, v117
	v_lshl_add_u32 v110, v0, 2, 0
	v_lshlrev_b32_e32 v0, 1, v0
	s_ashr_i32 s8, s28, 1
	v_add_u32_e32 v4, s7, v0
	v_add_u32_e32 v0, s6, v0
	s_lshl_b32 s6, s8, 12
	s_ashr_i32 s7, s6, 31
	s_lshl_b32 s5, s34, 1
	v_add3_u32 v108, s12, v113, v117
	s_lshl_b64 s[6:7], s[6:7], 1
	v_readlane_b32 s12, v254, 59
	s_add_u32 s6, s12, s6
	v_readlane_b32 s12, v254, 60
	s_addc_u32 s7, s12, s7
	s_cmp_lt_u32 s28, 2
	s_cselect_b64 s[40:41], -1, 0
	s_cmp_eq_u32 s8, 1
	s_cselect_b64 s[28:29], -1, 0
	s_cmp_eq_u32 s8, 2
	s_cselect_b64 s[30:31], -1, 0
	s_and_b32 s12, s0, 8
	s_cmp_lt_i32 s13, 0
	s_cselect_b32 s0, s34, s13
	s_mul_hi_i32 s8, s0, 0x38e38e39
	s_ashr_i32 s13, s8, 5
	s_lshr_b32 s14, s8, 31
	s_ashr_i32 s8, s8, 3
	s_add_i32 s8, s8, s14
	s_add_i32 s13, s13, s14
	s_and_b32 s14, s8, 3
	s_mul_i32 s8, s8, 36
	s_or_b32 s49, s12, 6
	s_sub_i32 s0, s0, s8
	s_lshl_b32 s15, s13, 11
	s_lshl_b32 s8, s13, 8
	s_or_b64 s[34:35], s[40:41], s[30:31]
	s_lshl_b32 s42, s49, 2
	s_lshl_b32 s33, s0, 6
	s_add_i32 s44, s15, 0xffffff00
	s_add_i32 s13, s8, 0x4000
	s_lshl_b32 s8, s14, 6
	s_xor_b64 s[36:37], s[34:35], -1
	s_lshl_b32 s45, s12, 3
	s_or_b32 s48, s12, 4
	s_and_b32 s50, s42, 48
	v_mul_u32_u24_e32 v9, 0x48, v109
	s_cmp_lt_i32 s0, 4
	v_and_b32_e32 v2, 0xffffffc, v61
	v_lshlrev_b32_e32 v9, 1, v9
	v_or_b32_e32 v2, s14, v2
	v_add_u32_e32 v11, 0x900, v9
	s_cselect_b32 s14, s13, s15
	s_cselect_b32 s13, s13, s44
	s_movk_i32 s15, 0x7ff
	v_add_u32_e32 v6, v69, v65
	v_add_u32_e32 v61, v4, v9
	v_add_u32_e32 v111, v0, v9
	v_add_u32_e32 v112, v4, v11
	v_add_u32_e32 v114, v0, v11
	v_add_u32_e32 v11, 0x1200, v9
	v_add_u32_e32 v9, 0x1b00, v9
	s_cselect_b32 s15, 0xff, s15
	s_add_i32 s13, s13, s33
	s_movk_i32 s0, 0x60
	v_add_u32_e32 v115, v4, v11
	v_add_u32_e32 v118, v4, v9
	v_lshl_add_u32 v4, v6, 4, s13
	v_lshlrev_b32_e32 v5, 1, v2
	v_mul_lo_u32 v2, v6, s0
	v_or_b32_e32 v10, 16, v109
	v_add_u32_e32 v15, -2, v4
	s_add_i32 s15, s15, s14
	v_mad_u32_u24 v122, v10, s92, 0
	v_and_b32_e32 v8, 4, v17
	v_sub_u32_e32 v2, v57, v2
	v_lshlrev_b32_e32 v3, 1, v2
	v_lshlrev_b32_e32 v2, 3, v2
	v_add_u32_e32 v116, v0, v11
	v_add_u32_e32 v119, v0, v9
	v_or_b32_e32 v0, s12, v13
	v_and_b32_e32 v3, 62, v3
	v_and_b32_e32 v2, 0xffffff00, v2
	s_mul_i32 s0, s12, 0x240
	v_lshlrev_b32_e32 v120, 3, v0
	v_or_b32_e32 v0, s48, v13
	v_or3_b32 v2, v2, s8, v3
	v_lshlrev_b32_e32 v13, 3, v0
	v_or_b32_e32 v0, s13, v53
	v_mov_b64_e32 v[18:19], s[16:17]
	v_ashrrev_i32_e32 v3, 31, v2
	v_add_u32_e32 v9, 0x900, v122
	v_add_u32_e32 v11, 0x1200, v122
	v_lshl_add_u64 v[2:3], v[2:3], 1, s[16:17]
	s_mov_b32 s9, 0
	v_lshlrev_b32_e32 v12, 3, v53
	v_lshl_or_b32 v60, s12, 8, v12
	v_and_b32_e32 v6, 16, v7
	s_lshl_b32 s12, s49, 8
	v_or3_b32 v4, v6, s45, v109
	v_or3_b32 v6, v109, v6, s45
	s_and_b32 s12, s12, 0xc00
	v_lshl_or_b32 v4, v4, 3, v8
	v_lshl_or_b32 v62, v6, 3, v8
	v_lshl_or_b32 v6, s48, 8, v12
	v_or_b32_e32 v12, s12, v12
	v_mad_i64_i32 v[18:19], s[12:13], v0, s66, v[18:19]
	v_add_u32_e32 v0, 0x1800, v5
	v_or_b32_e32 v8, 0x100, v4
	v_or_b32_e32 v10, 0x500, v4
	v_or_b32_e32 v14, 0x900, v4
	v_or_b32_e32 v16, 0xd00, v4
	v_lshl_add_u64 v[64:65], v[18:19], 0, v[0:1]
	v_add_u32_e32 v0, 0x1810, v5
	s_mov_b64 s[46:47], -1
	v_cmp_eq_u32_e64 s[42:43], 0, v57
	s_mul_i32 s8, s50, 0x90
	v_lshl_add_u64 v[66:67], v[18:19], 0, v[0:1]
	s_mov_b64 s[98:99], exec
	s_and_b64 exec, exec, s[38:39]
	s_cbranch_execz .Lgate_pf
	global_load_ushort v220, v[64:65], off
	global_load_ushort v221, v[66:67], off
.Lgate_pf:
	s_mov_b64 exec, s[98:99]
	v_mad_i64_i32 v[68:69], s[12:13], v15, s66, v[2:3]
	s_mov_b32 s98, s66
	s_mov_b32 s99, 0
	v_lshl_add_u64 v[70:71], v[68:69], 0, s[98:99]
	v_lshl_add_u64 v[72:73], v[70:71], 0, s[98:99]
	v_lshl_add_u64 v[74:75], v[72:73], 0, s[98:99]
	v_lshl_add_u64 v[76:77], v[74:75], 0, s[98:99]
	v_lshl_add_u64 v[78:79], v[76:77], 0, s[98:99]
	v_lshl_add_u64 v[80:81], v[78:79], 0, s[98:99]
	v_lshl_add_u64 v[82:83], v[80:81], 0, s[98:99]
	v_lshl_add_u64 v[84:85], v[82:83], 0, s[98:99]
	v_lshl_add_u64 v[86:87], v[84:85], 0, s[98:99]
	v_lshl_add_u64 v[88:89], v[86:87], 0, s[98:99]
	v_lshl_add_u64 v[90:91], v[88:89], 0, s[98:99]
	v_lshl_add_u64 v[92:93], v[90:91], 0, s[98:99]
	v_lshl_add_u64 v[94:95], v[92:93], 0, s[98:99]
	v_lshl_add_u64 v[96:97], v[94:95], 0, s[98:99]
	v_lshl_add_u64 v[98:99], v[96:97], 0, s[98:99]
	v_lshl_add_u64 v[100:101], v[98:99], 0, s[98:99]
	v_lshl_add_u64 v[102:103], v[100:101], 0, s[98:99]
	v_lshl_add_u64 v[104:105], v[102:103], 0, s[98:99]
	v_lshl_add_u64 v[106:107], v[104:105], 0, s[98:99]
	v_add_u32_e32 v123, v121, v13
	v_lshlrev_b32_e32 v124, 1, v4
	v_lshlrev_b32_e32 v125, 1, v6
	v_lshlrev_b32_e32 v126, 1, v8
	v_lshlrev_b32_e32 v127, 1, v12
	v_lshlrev_b32_e32 v128, 1, v10
	v_lshlrev_b32_e32 v129, 1, v14
	v_lshlrev_b32_e32 v130, 1, v16
	v_add_u32_e32 v131, v9, v120
	v_add_u32_e32 v132, v11, v120
	s_waitcnt lgkmcnt(0)
	s_barrier
	s_branch .LBB0_646

; __device__ __forceinline__ v2u pack4(const f32x4 v) { v2u r; r.x = pk2(v[0], v[1]); r.y = pk2(v[2], v[3]); return r; }
; __device__ __forceinline__ void gdn_preload(const Frame& F, int u, int t, GdnPre& P) {
;     ...
;     } else {
;         const int tt = t - 384, d = tt >> 6, pp = tt & 63; const bf16_t* zr = F.Z + (size_t)(row0 + pp) * ZW;
;         P.ga = zr[ZC_GA + d * 4 + h]; P.gb = zr[ZC_GB + d * 4 + h];
;     ...
;                 if (prod == 0) acc = -acc;
;                 res[k8] = pack4(acc); }
.LBB0_662:
	s_nop 2
	v_xor_b32_e32 v0, 0x80000000, v36
	v_xor_b32_e32 v10, 0x80000000, v37
	v_xor_b32_e32 v11, 0x80000000, v38
	v_xor_b32_e32 v32, 0x80000000, v39
	v_cndmask_b32_e64 v32, v39, v32, s[40:41]
	v_cndmask_b32_e64 v11, v38, v11, s[40:41]
	v_cndmask_b32_e64 v10, v37, v10, s[40:41]
	v_cndmask_b32_e64 v0, v36, v0, s[40:41]
	v_cvt_pk_bf16_f32 v10, v0, v10
	v_cvt_pk_bf16_f32 v11, v11, v32
	v_xor_b32_e32 v0, 0x80000000, v16
	v_xor_b32_e32 v32, 0x80000000, v17
	v_xor_b32_e32 v33, 0x80000000, v18
	v_cndmask_b32_e64 v17, v17, v32, s[40:41]
	v_cndmask_b32_e64 v0, v16, v0, s[40:41]
	v_cndmask_b32_e64 v33, v18, v33, s[40:41]
	v_cvt_pk_bf16_f32 v18, v0, v17
	v_xor_b32_e32 v0, 0x80000000, v24
	v_xor_b32_e32 v16, 0x80000000, v25
	v_cndmask_b32_e64 v16, v25, v16, s[40:41]
	v_cndmask_b32_e64 v0, v24, v0, s[40:41]
	v_cvt_pk_bf16_f32 v16, v0, v16
	v_xor_b32_e32 v0, 0x80000000, v20
	v_xor_b32_e32 v24, 0x80000000, v21
	v_xor_b32_e32 v25, 0x80000000, v22
	v_cndmask_b32_e64 v21, v21, v24, s[40:41]
	v_cndmask_b32_e64 v0, v20, v0, s[40:41]
	v_cndmask_b32_e64 v25, v22, v25, s[40:41]
	v_cvt_pk_bf16_f32 v22, v0, v21
	v_xor_b32_e32 v0, 0x80000000, v12
	v_xor_b32_e32 v20, 0x80000000, v13
	v_xor_b32_e32 v21, 0x80000000, v14
	v_xor_b32_e32 v24, 0x80000000, v15
	v_cndmask_b32_e64 v15, v15, v24, s[40:41]
	v_cndmask_b32_e64 v14, v14, v21, s[40:41]
	v_cndmask_b32_e64 v13, v13, v20, s[40:41]
	v_cndmask_b32_e64 v0, v12, v0, s[40:41]
	v_cvt_pk_bf16_f32 v20, v0, v13
	v_cvt_pk_bf16_f32 v21, v14, v15
	v_xor_b32_e32 v0, 0x80000000, v6
	v_xor_b32_e32 v12, 0x80000000, v7
	v_xor_b32_e32 v13, 0x80000000, v8
	v_xor_b32_e32 v14, 0x80000000, v9
	v_cndmask_b32_e64 v9, v9, v14, s[40:41]
	v_cndmask_b32_e64 v8, v8, v13, s[40:41]
	v_cndmask_b32_e64 v7, v7, v12, s[40:41]
	v_cndmask_b32_e64 v0, v6, v0, s[40:41]
	v_cvt_pk_bf16_f32 v6, v0, v7
	v_cvt_pk_bf16_f32 v7, v8, v9
	v_xor_b32_e32 v0, 0x80000000, v2
	v_xor_b32_e32 v8, 0x80000000, v3
	v_xor_b32_e32 v17, 0x80000000, v26
	v_xor_b32_e32 v9, 0x80000000, v4
	v_cndmask_b32_e64 v3, v3, v8, s[40:41]
	v_cndmask_b32_e64 v0, v2, v0, s[40:41]
	v_xor_b32_e32 v34, 0x80000000, v19
	v_xor_b32_e32 v32, 0x80000000, v27
	v_cndmask_b32_e64 v17, v26, v17, s[40:41]
	v_xor_b32_e32 v26, 0x80000000, v23
	v_xor_b32_e32 v12, 0x80000000, v5
	v_cndmask_b32_e64 v9, v4, v9, s[40:41]
	v_cvt_pk_bf16_f32 v4, v0, v3
	v_xor_b32_e32 v0, 0x80000000, v28
	v_xor_b32_e32 v2, 0x80000000, v29
	v_xor_b32_e32 v3, 0x80000000, v30
	v_xor_b32_e32 v8, 0x80000000, v31
	v_cndmask_b32_e64 v19, v19, v34, s[40:41]
	v_cndmask_b32_e64 v27, v27, v32, s[40:41]
	v_cndmask_b32_e64 v23, v23, v26, s[40:41]
	v_cndmask_b32_e64 v5, v5, v12, s[40:41]
	v_cndmask_b32_e64 v8, v31, v8, s[40:41]
	v_cndmask_b32_e64 v3, v30, v3, s[40:41]
	v_cndmask_b32_e64 v2, v29, v2, s[40:41]
	v_cndmask_b32_e64 v0, v28, v0, s[40:41]
	v_cvt_pk_bf16_f32 v19, v33, v19
	v_cvt_pk_bf16_f32 v17, v17, v27
	v_cvt_pk_bf16_f32 v23, v25, v23
	v_cvt_pk_bf16_f32 v5, v9, v5
	v_cvt_pk_bf16_f32 v12, v0, v2
	v_cvt_pk_bf16_f32 v13, v3, v8
	s_and_saveexec_b64 s[12:13], s[38:39]
	s_xor_b64 s[12:13], exec, s[12:13]
	s_cbranch_execz .LBB0_664
	s_waitcnt vmcnt(0)
	v_mov_b32_e32 v2, v220
	v_mov_b32_e32 v3, v221
